# prompt attention epilogue: half-wave exchange (v_permlane32_swap) and four 16-byte stores per head instead of eight 8-byte ones
# speedup vs baseline: 1.0111x; 1.0058x over previous
.LBB0_2055:
	s_or_b64 exec, exec, s[0:1]
	v_writelane_b32 v254, s24, 52
	s_and_b32 s0, s24, 0xfffff000
	v_writelane_b32 v254, s0, 53
	s_and_b32 s0, s20, 0xf80
	s_lshl_b32 s46, s16, 3
	s_lshl_b32 s36, s16, 5
	v_writelane_b32 v254, s0, 54
	s_lshl_b32 s0, s16, 10
	v_writelane_b32 v254, s0, 55
	v_and_b32_e32 v101, 31, v25
	s_add_u32 s0, s26, 0x96e0000
	v_ashrrev_i32_e32 v10, 1, v27
	s_addc_u32 s1, s27, 0
	v_and_b32_e32 v11, 0xffffffe0, v10
	v_or_b32_e32 v4, s19, v101
	v_writelane_b32 v254, s0, 56
	v_add_u32_e32 v98, v4, v11
	v_ashrrev_i32_e32 v99, 31, v98
	v_writelane_b32 v254, s1, 57
	s_mul_i32 s0, s18, 0x8100
	s_mov_b32 s1, s37
	v_bfe_u32 v7, v25, 5, 1
	v_lshl_add_u64 v[4:5], v[98:99], 0, s[0:1]
	s_lshl_b32 s0, s18, 3
	v_lshlrev_b32_e32 v100, 2, v7
	s_cmp_eq_u32 s17, 0
	v_sub_u32_e32 v8, 0x80, v11
	v_writelane_b32 v254, s0, 36
	s_cselect_b64 s[0:1], -1, 0
	v_cmp_lt_i32_e32 vcc, v100, v8
	s_and_b64 s[2:3], s[0:1], vcc
	v_or_b32_e32 v9, 1, v100
	v_writelane_b32 v254, s2, 37
	v_cmp_lt_i32_e32 vcc, v9, v8
	v_or_b32_e32 v104, 2, v100
	v_writelane_b32 v254, s3, 38
	s_and_b64 s[2:3], s[0:1], vcc
	v_writelane_b32 v254, s2, 39
	v_cmp_lt_i32_e32 vcc, v104, v8
	v_or_b32_e32 v105, 3, v100
	v_writelane_b32 v254, s3, 40
	s_and_b64 s[2:3], s[0:1], vcc
	v_writelane_b32 v254, s2, 20
	v_cmp_lt_i32_e32 vcc, v105, v8
	v_or_b32_e32 v106, 8, v100
	v_writelane_b32 v254, s3, 21
	s_and_b64 s[2:3], s[0:1], vcc
	v_writelane_b32 v254, s2, 18
	v_cmp_lt_i32_e32 vcc, v106, v8
	v_or_b32_e32 v107, 9, v100
	v_writelane_b32 v254, s3, 19
	s_and_b64 s[2:3], s[0:1], vcc
	v_writelane_b32 v254, s2, 41
	v_cmp_lt_i32_e32 vcc, v107, v8
	v_or_b32_e32 v108, 10, v100
	v_writelane_b32 v254, s3, 42
	s_and_b64 s[2:3], s[0:1], vcc
	v_writelane_b32 v254, s2, 22
	v_cmp_lt_i32_e32 vcc, v108, v8
	v_or_b32_e32 v109, 11, v100
	v_writelane_b32 v254, s3, 23
	s_and_b64 s[2:3], s[0:1], vcc
	v_writelane_b32 v254, s2, 24
	v_cmp_lt_i32_e32 vcc, v109, v8
	v_or_b32_e32 v110, 16, v100
	v_writelane_b32 v254, s3, 25
	s_and_b64 s[2:3], s[0:1], vcc
	v_writelane_b32 v254, s2, 26
	v_cmp_lt_i32_e32 vcc, v110, v8
	v_or_b32_e32 v111, 17, v100
	v_writelane_b32 v254, s3, 27
	s_and_b64 s[2:3], s[0:1], vcc
	v_writelane_b32 v254, s2, 28
	v_cmp_lt_i32_e32 vcc, v111, v8
	v_or_b32_e32 v112, 18, v100
	v_writelane_b32 v254, s3, 29
	s_and_b64 s[2:3], s[0:1], vcc
	v_writelane_b32 v254, s2, 32
	v_cmp_lt_i32_e32 vcc, v112, v8
	v_or_b32_e32 v113, 19, v100
	v_writelane_b32 v254, s3, 33
	s_and_b64 s[2:3], s[0:1], vcc
	v_writelane_b32 v254, s2, 34
	v_cmp_lt_i32_e32 vcc, v113, v8
	v_or_b32_e32 v114, 24, v100
	v_writelane_b32 v254, s3, 35
	s_and_b64 s[2:3], s[0:1], vcc
	v_writelane_b32 v254, s2, 5
	v_cmp_lt_i32_e32 vcc, v114, v8
	v_or_b32_e32 v115, 25, v100
	v_writelane_b32 v254, s3, 6
	s_and_b64 s[2:3], s[0:1], vcc
	v_writelane_b32 v254, s2, 8
	v_cmp_lt_i32_e32 vcc, v115, v8
	v_or_b32_e32 v116, 26, v100
	v_writelane_b32 v254, s3, 9
	s_and_b64 s[2:3], s[0:1], vcc
	v_writelane_b32 v254, s2, 30
	v_cmp_lt_i32_e32 vcc, v116, v8
	v_or_b32_e32 v117, 27, v100
	v_writelane_b32 v254, s3, 31
	s_and_b64 s[2:3], s[0:1], vcc
	v_writelane_b32 v254, s2, 58
	v_cmp_lt_i32_e32 vcc, v117, v8
	v_or_b32_e32 v9, 32, v100
	v_writelane_b32 v254, s3, 59
	s_and_b64 s[2:3], s[0:1], vcc
	v_writelane_b32 v254, s2, 60
	v_cmp_lt_i32_e32 vcc, v9, v8
	v_or_b32_e32 v9, 33, v100
	v_writelane_b32 v254, s3, 61
	s_and_b64 s[2:3], s[0:1], vcc
	v_writelane_b32 v254, s2, 62
	v_or_b32_e32 v118, 0x80, v100
	v_cmp_lt_i32_e32 vcc, v118, v8
	v_writelane_b32 v254, s3, 63
	v_cmp_lt_i32_e64 s[2:3], v9, v8
	s_and_b64 s[2:3], s[0:1], s[2:3]
	v_or_b32_e32 v9, 34, v100
	v_writelane_b32 v255, s2, 0
	v_cmp_lt_i32_e64 s[4:5], v9, v8
	v_or_b32_e32 v9, 35, v100
	v_writelane_b32 v255, s3, 1
	s_and_b64 s[2:3], s[0:1], s[4:5]
	v_writelane_b32 v255, s2, 2
	v_cmp_lt_i32_e64 s[6:7], v9, v8
	v_or_b32_e32 v9, 40, v100
	v_writelane_b32 v255, s3, 3
	s_and_b64 s[2:3], s[0:1], s[6:7]
	v_writelane_b32 v255, s2, 4
	v_cmp_lt_i32_e64 s[8:9], v9, v8
	v_or_b32_e32 v9, 41, v100
	v_writelane_b32 v255, s3, 5
	s_and_b64 s[2:3], s[0:1], s[8:9]
	v_writelane_b32 v255, s2, 6
	v_cmp_lt_i32_e64 s[10:11], v9, v8
	v_or_b32_e32 v9, 42, v100
	v_writelane_b32 v255, s3, 7
	s_and_b64 s[2:3], s[0:1], s[10:11]
	v_writelane_b32 v255, s2, 8
	v_cmp_lt_i32_e64 s[12:13], v9, v8
	v_or_b32_e32 v9, 43, v100
	v_writelane_b32 v255, s3, 9
	s_and_b64 s[2:3], s[0:1], s[12:13]
	v_writelane_b32 v255, s2, 10
	v_cmp_lt_i32_e64 s[14:15], v9, v8
	v_or_b32_e32 v9, 48, v100
	v_writelane_b32 v255, s3, 11
	s_and_b64 s[2:3], s[0:1], s[14:15]
	v_writelane_b32 v255, s2, 12
	v_cmp_lt_i32_e64 s[16:17], v9, v8
	v_or_b32_e32 v9, 49, v100
	v_writelane_b32 v255, s3, 13
	s_and_b64 s[2:3], s[0:1], s[16:17]
	v_writelane_b32 v255, s2, 14
	v_cmp_lt_i32_e64 s[18:19], v9, v8
	v_or_b32_e32 v9, 50, v100
	v_writelane_b32 v255, s3, 15
	s_and_b64 s[2:3], s[0:1], s[18:19]
	v_writelane_b32 v255, s2, 16
	v_cmp_lt_i32_e64 s[20:21], v9, v8
	v_or_b32_e32 v9, 51, v100
	v_writelane_b32 v255, s3, 17
	s_and_b64 s[2:3], s[0:1], s[20:21]
	v_writelane_b32 v255, s2, 18
	v_cmp_lt_i32_e64 s[22:23], v9, v8
	v_or_b32_e32 v9, 56, v100
	v_writelane_b32 v255, s3, 19
	s_and_b64 s[2:3], s[0:1], s[22:23]
	v_writelane_b32 v255, s2, 20
	v_cmp_lt_i32_e64 s[24:25], v9, v8
	v_or_b32_e32 v9, 57, v100
	v_writelane_b32 v255, s3, 21
	s_and_b64 s[2:3], s[0:1], s[24:25]
	v_writelane_b32 v255, s2, 22
	s_mov_b64 s[6:7], s[26:27]
	v_cmp_lt_i32_e64 s[26:27], v9, v8
	v_writelane_b32 v255, s3, 23
	s_and_b64 s[2:3], s[0:1], s[26:27]
	v_or_b32_e32 v9, 58, v100
	v_writelane_b32 v255, s2, 24
	v_cmp_lt_i32_e64 s[28:29], v9, v8
	v_or_b32_e32 v9, 59, v100
	v_writelane_b32 v255, s3, 25
	s_and_b64 s[2:3], s[0:1], s[28:29]
	v_writelane_b32 v255, s2, 26
	v_cmp_lt_i32_e64 s[30:31], v9, v8
	v_or_b32_e32 v9, 64, v100
	v_writelane_b32 v255, s3, 27
	s_and_b64 s[2:3], s[0:1], s[30:31]
	v_writelane_b32 v255, s2, 28
	v_cmp_lt_i32_e64 s[34:35], v9, v8
	v_or_b32_e32 v9, 0x41, v100
	v_writelane_b32 v255, s3, 29
	s_and_b64 s[2:3], s[0:1], s[34:35]
	v_writelane_b32 v255, s2, 30
	v_or_b32_e32 v119, 0x81, v100
	v_or_b32_e32 v120, 0x82, v100
	v_writelane_b32 v255, s3, 31
	s_mov_b64 s[2:3], s[36:37]
	v_cmp_lt_i32_e64 s[36:37], v9, v8
	s_and_b64 s[4:5], s[0:1], s[36:37]
	v_or_b32_e32 v9, 0x42, v100
	v_writelane_b32 v255, s4, 32
	v_cmp_lt_i32_e64 s[38:39], v9, v8
	v_or_b32_e32 v9, 0x43, v100
	v_writelane_b32 v255, s5, 33
	s_and_b64 s[4:5], s[0:1], s[38:39]
	v_writelane_b32 v255, s4, 34
	v_cmp_lt_i32_e64 s[40:41], v9, v8
	v_or_b32_e32 v9, 0x48, v100
	v_writelane_b32 v255, s5, 35
	s_and_b64 s[4:5], s[0:1], s[40:41]
	v_writelane_b32 v255, s4, 36
	v_cmp_lt_i32_e64 s[42:43], v9, v8
	v_or_b32_e32 v9, 0x49, v100
	v_writelane_b32 v255, s5, 37
	s_and_b64 s[4:5], s[0:1], s[42:43]
	v_writelane_b32 v255, s4, 38
	v_cmp_lt_i32_e64 s[44:45], v9, v8
	v_or_b32_e32 v9, 0x4a, v100
	v_writelane_b32 v255, s5, 39
	s_and_b64 s[4:5], s[0:1], s[44:45]
	s_mov_b32 s45, s46
	v_cmp_lt_i32_e64 s[46:47], v9, v8
	v_or_b32_e32 v9, 0x4b, v100
	v_cmp_lt_i32_e64 s[48:49], v9, v8
	v_or_b32_e32 v9, 0x50, v100
	v_cmp_lt_i32_e64 s[50:51], v9, v8
	v_or_b32_e32 v9, 0x51, v100
	v_cmp_lt_i32_e64 s[52:53], v9, v8
	v_or_b32_e32 v9, 0x52, v100
	v_cmp_lt_i32_e64 s[54:55], v9, v8
	v_or_b32_e32 v9, 0x53, v100
	v_cmp_lt_i32_e64 s[56:57], v9, v8
	v_or_b32_e32 v9, 0x58, v100
	v_cmp_lt_i32_e64 s[58:59], v9, v8
	v_or_b32_e32 v9, 0x59, v100
	v_cmp_lt_i32_e64 s[60:61], v9, v8
	v_or_b32_e32 v9, 0x5a, v100
	v_cmp_lt_i32_e64 s[62:63], v9, v8
	v_or_b32_e32 v9, 0x5b, v100
	v_writelane_b32 v255, s4, 40
	v_cmp_lt_i32_e64 s[64:65], v9, v8
	v_or_b32_e32 v9, 0x60, v100
	v_writelane_b32 v255, s5, 41
	s_and_b64 s[4:5], s[0:1], s[46:47]
	v_cmp_lt_i32_e64 s[66:67], v9, v8
	v_or_b32_e32 v9, 0x61, v100
	v_writelane_b32 v255, s4, 42
	v_cmp_lt_i32_e64 s[68:69], v9, v8
	v_or_b32_e32 v9, 0x62, v100
	s_and_b64 s[42:43], s[0:1], vcc
	v_cmp_lt_i32_e32 vcc, v119, v8
	v_writelane_b32 v255, s5, 43
	v_cmp_lt_i32_e64 s[70:71], v9, v8
	v_or_b32_e32 v9, 0x63, v100
	s_and_b64 s[4:5], s[0:1], vcc
	v_cmp_lt_i32_e32 vcc, v120, v8
	v_or_b32_e32 v121, 0x83, v100
	s_and_b64 s[36:37], s[0:1], s[48:49]
	v_cmp_lt_i32_e64 s[72:73], v9, v8
	v_or_b32_e32 v9, 0x68, v100
	s_and_b64 s[48:49], s[0:1], vcc
	v_cmp_lt_i32_e32 vcc, v121, v8
	v_or_b32_e32 v122, 0x88, v100
	v_cmp_lt_i32_e64 s[74:75], v9, v8
	v_or_b32_e32 v9, 0x69, v100
	s_and_b64 s[8:9], s[0:1], vcc
	v_cmp_lt_i32_e32 vcc, v122, v8
	v_or_b32_e32 v123, 0x89, v100
	v_cmp_lt_i32_e64 s[76:77], v9, v8
	v_or_b32_e32 v9, 0x6a, v100
	s_and_b64 s[10:11], s[0:1], vcc
	v_cmp_lt_i32_e32 vcc, v123, v8
	v_or_b32_e32 v124, 0x8a, v100
	v_cmp_lt_i32_e64 s[78:79], v9, v8
	v_or_b32_e32 v9, 0x6b, v100
	s_and_b64 s[12:13], s[0:1], vcc
	v_cmp_lt_i32_e32 vcc, v124, v8
	v_or_b32_e32 v125, 0x8b, v100
	v_cmp_lt_i32_e64 s[80:81], v9, v8
	v_or_b32_e32 v9, 0x70, v100
	s_and_b64 s[14:15], s[0:1], vcc
	v_cmp_lt_i32_e32 vcc, v125, v8
	v_or_b32_e32 v126, 0x90, v100
	v_cmp_lt_i32_e64 s[82:83], v9, v8
	v_or_b32_e32 v9, 0x71, v100
	s_and_b64 s[16:17], s[0:1], vcc
	v_cmp_lt_i32_e32 vcc, v126, v8
	v_or_b32_e32 v127, 0x91, v100
	v_cmp_lt_i32_e64 s[84:85], v9, v8
	v_or_b32_e32 v9, 0x72, v100
	s_and_b64 s[18:19], s[0:1], vcc
	v_cmp_lt_i32_e32 vcc, v127, v8
	v_or_b32_e32 v128, 0x92, v100
	v_cmp_lt_i32_e64 s[86:87], v9, v8
	v_or_b32_e32 v9, 0x73, v100
	s_and_b64 s[20:21], s[0:1], vcc
	v_cmp_lt_i32_e32 vcc, v128, v8
	v_or_b32_e32 v129, 0x93, v100
	v_cmp_lt_i32_e64 s[88:89], v9, v8
	v_or_b32_e32 v9, 0x78, v100
	s_and_b64 s[22:23], s[0:1], vcc
	v_cmp_lt_i32_e32 vcc, v129, v8
	v_or_b32_e32 v130, 0x98, v100
	v_cmp_lt_i32_e64 s[90:91], v9, v8
	v_or_b32_e32 v9, 0x79, v100
	s_and_b64 s[24:25], s[0:1], vcc
	v_cmp_lt_i32_e32 vcc, v130, v8
	v_or_b32_e32 v131, 0x99, v100
	v_cmp_lt_i32_e64 s[92:93], v9, v8
	v_or_b32_e32 v9, 0x7a, v100
	s_and_b64 s[26:27], s[0:1], vcc
	v_cmp_lt_i32_e32 vcc, v131, v8
	v_or_b32_e32 v132, 0x9a, v100
	v_cmp_lt_i32_e64 s[94:95], v9, v8
	v_or_b32_e32 v9, 0x7b, v100
	s_and_b64 s[28:29], s[0:1], vcc
	v_cmp_lt_i32_e32 vcc, v132, v8
	v_or_b32_e32 v133, 0x9b, v100
	v_cmp_lt_i32_e64 s[96:97], v9, v8
	s_and_b64 s[30:31], s[0:1], vcc
	v_cmp_lt_i32_e32 vcc, v133, v8
	s_and_b64 s[50:51], s[0:1], s[50:51]
	s_and_b64 s[52:53], s[0:1], s[52:53]
	s_and_b64 s[54:55], s[0:1], s[54:55]
	s_and_b64 s[56:57], s[0:1], s[56:57]
	s_and_b64 s[58:59], s[0:1], s[58:59]
	s_and_b64 s[60:61], s[0:1], s[60:61]
	s_and_b64 s[62:63], s[0:1], s[62:63]
	s_and_b64 s[64:65], s[0:1], s[64:65]
	s_and_b64 s[66:67], s[0:1], s[66:67]
	s_and_b64 s[68:69], s[0:1], s[68:69]
	s_and_b64 s[70:71], s[0:1], s[70:71]
	s_and_b64 s[72:73], s[0:1], s[72:73]
	s_and_b64 s[74:75], s[0:1], s[74:75]
	s_and_b64 s[76:77], s[0:1], s[76:77]
	s_and_b64 s[78:79], s[0:1], s[78:79]
	s_and_b64 s[80:81], s[0:1], s[80:81]
	s_and_b64 s[82:83], s[0:1], s[82:83]
	s_and_b64 s[84:85], s[0:1], s[84:85]
	s_and_b64 s[86:87], s[0:1], s[86:87]
	s_and_b64 s[88:89], s[0:1], s[88:89]
	s_and_b64 s[90:91], s[0:1], s[90:91]
	s_and_b64 s[92:93], s[0:1], s[92:93]
	s_and_b64 s[94:95], s[0:1], s[94:95]
	s_and_b64 s[96:97], s[0:1], s[96:97]
	s_and_b64 s[34:35], s[0:1], vcc
	v_readlane_b32 s0, v254, 53
	v_readlane_b32 s1, v254, 54
	s_or_b32 s0, s0, s1
	v_add_u32_e32 v8, s0, v11
	v_or_b32_e32 v8, v8, v101
	v_ashrrev_i32_e32 v9, 31, v8
	v_lshlrev_b32_e32 v134, 3, v7
	v_lshlrev_b64 v[8:9], 12, v[8:9]
	v_readlane_b32 s0, v254, 55
	v_lshl_add_u32 v6, v26, 1, v6
	s_waitcnt vmcnt(0)
	ds_write_b16 v6, v0 offset:36864
	ds_write_b16_d16_hi v6, v0 offset:37400
	ds_write_b16 v6, v1 offset:37936
	ds_write_b16_d16_hi v6, v1 offset:38472
	ds_write_b16 v6, v2 offset:39008
	ds_write_b16_d16_hi v6, v2 offset:39544
	ds_write_b16 v6, v3 offset:40080
	ds_write_b16_d16_hi v6, v3 offset:40616
	v_or3_b32 v8, v8, s0, v134
	v_readlane_b32 s0, v254, 56
	v_lshlrev_b64 v[0:1], 9, v[4:5]
	v_readlane_b32 s1, v254, 57
	v_lshlrev_b32_e32 v96, 4, v7
	s_waitcnt lgkmcnt(0)
	v_lshl_add_u64 v[0:1], s[0:1], 0, v[0:1]
	v_lshl_add_u64 v[0:1], v[0:1], 0, v[96:97]
	s_barrier
	global_load_dwordx4 v[80:83], v[0:1], off
	global_load_dwordx4 v[84:87], v[0:1], off offset:32
	global_load_dwordx4 v[88:91], v[0:1], off offset:64
	global_load_dwordx4 v[92:95], v[0:1], off offset:96
	s_mov_b64 s[46:47], s[0:1]
	s_movk_i32 s0, 0xffe0
	v_bfi_b32 v0, s0, v10, v25
	v_readlane_b32 s0, v254, 17
	v_lshlrev_b32_e32 v2, 1, v11
	s_movk_i32 s1, 0x90
	v_lshl_add_u64 v[8:9], s[6:7], 0, v[8:9]
	v_add_u32_e32 v1, s0, v96
	v_mul_lo_u32 v0, v0, s1
	v_mul_u32_u24_e32 v3, 0x218, v101
	v_add3_u32 v2, s0, v2, v134
	s_mov_b64 s[0:1], 0x15860040
	v_readlane_b32 s40, v254, 15
	s_mov_b64 s[6:7], s[36:37]
	v_lshl_add_u64 v[102:103], v[8:9], 0, s[0:1]
	v_add_u32_e32 v135, v1, v0
	v_add_u32_e32 v136, v2, v3
	s_mov_b32 s38, 0
	s_mov_b64 s[36:37], s[2:3]
	v_readlane_b32 s41, v254, 16
	v_readlane_b32 s44, v254, 50
	v_mbcnt_lo_u32_b32 v206, -1, 0
	v_mbcnt_hi_u32_b32 v206, -1, v206
	v_lshrrev_b32_e32 v206, 5, v206
	v_lshlrev_b32_e32 v206, 3, v206
	v_mov_b32_e32 v207, 0
	s_waitcnt vmcnt(0)
.LBB0_2056:
	v_mov_b32_e32 v96, v101
	ds_read_b128 v[0:3], v135
	ds_read_b128 v[4:7], v135 offset:32
	s_load_dwordx2 s[0:1], s[40:41], 0x80
	s_add_i32 s39, s45, s38
	s_waitcnt lgkmcnt(0)
	v_mfma_f32_32x32x16_bf16 v[64:79], v[0:3], v[80:83], 0
	ds_read_b128 v[0:3], v135 offset:64
	s_add_u32 s0, s0, s36
	s_addc_u32 s1, s1, s37
	s_add_i32 s38, s38, 1
	s_nop 0
	v_mfma_f32_32x32x16_bf16 v[64:79], v[4:7], v[84:87], v[64:79]
	s_waitcnt lgkmcnt(0)
	v_mfma_f32_32x32x16_bf16 v[64:79], v[0:3], v[88:91], v[64:79]
	ds_read_b128 v[0:3], v135 offset:96
	s_waitcnt lgkmcnt(0)
	v_mfma_f32_32x32x16_bf16 v[64:79], v[0:3], v[92:95], v[64:79]
	ds_read_b128 v[0:3], v135 offset:4608
	s_waitcnt lgkmcnt(0)
	v_mfma_f32_32x32x16_bf16 v[48:63], v[0:3], v[80:83], 0
	ds_read_b128 v[0:3], v135 offset:4640
	s_waitcnt lgkmcnt(0)
	v_mfma_f32_32x32x16_bf16 v[48:63], v[0:3], v[84:87], v[48:63]
	ds_read_b128 v[0:3], v135 offset:4672
	s_waitcnt lgkmcnt(0)
	v_mfma_f32_32x32x16_bf16 v[48:63], v[0:3], v[88:91], v[48:63]
	ds_read_b128 v[0:3], v135 offset:4704
	s_waitcnt lgkmcnt(0)
	v_mfma_f32_32x32x16_bf16 v[48:63], v[0:3], v[92:95], v[48:63]
	ds_read_b128 v[0:3], v135 offset:9216
	s_waitcnt lgkmcnt(0)
	v_mfma_f32_32x32x16_bf16 v[32:47], v[0:3], v[80:83], 0
	ds_read_b128 v[0:3], v135 offset:9248
	s_waitcnt lgkmcnt(0)
	v_mfma_f32_32x32x16_bf16 v[32:47], v[0:3], v[84:87], v[32:47]
	ds_read_b128 v[0:3], v135 offset:9280
	s_waitcnt lgkmcnt(0)
	v_mfma_f32_32x32x16_bf16 v[32:47], v[0:3], v[88:91], v[32:47]
	ds_read_b128 v[0:3], v135 offset:9312
	s_waitcnt lgkmcnt(0)
	v_mfma_f32_32x32x16_bf16 v[32:47], v[0:3], v[92:95], v[32:47]
	ds_read_b128 v[0:3], v135 offset:13824
	s_waitcnt lgkmcnt(0)
	v_mfma_f32_32x32x16_bf16 v[16:31], v[0:3], v[80:83], 0
	ds_read_b128 v[0:3], v135 offset:13856
	s_waitcnt lgkmcnt(0)
	v_mfma_f32_32x32x16_bf16 v[16:31], v[0:3], v[84:87], v[16:31]
	ds_read_b128 v[0:3], v135 offset:13888
	s_waitcnt lgkmcnt(0)
	v_mfma_f32_32x32x16_bf16 v[16:31], v[0:3], v[88:91], v[16:31]
	ds_read_b128 v[0:3], v135 offset:13920
	s_waitcnt lgkmcnt(0)
	v_mfma_f32_32x32x16_bf16 v[16:31], v[0:3], v[92:95], v[16:31]
	ds_read_b128 v[0:3], v135 offset:18432
	s_waitcnt lgkmcnt(0)
	v_mfma_f32_32x32x16_bf16 v[0:15], v[0:3], v[80:83], 0
	ds_read_b128 v[80:83], v135 offset:18464
	s_waitcnt lgkmcnt(0)
	v_mfma_f32_32x32x16_bf16 v[0:15], v[80:83], v[84:87], v[0:15]
	ds_read_b128 v[80:83], v135 offset:18496
	s_waitcnt lgkmcnt(0)
	v_mfma_f32_32x32x16_bf16 v[0:15], v[80:83], v[88:91], v[0:15]
	ds_read_b128 v[80:83], v135 offset:18528
	s_waitcnt lgkmcnt(0)
	v_mfma_f32_32x32x16_bf16 v[0:15], v[80:83], v[92:95], v[0:15]
	global_load_dword v80, v97, s[0:1]
	v_add_u32_e32 v94, 0x80, v96
	v_cmp_le_i32_e64 s[0:1], v100, v96
	v_cmp_gt_i32_e32 vcc, v100, v94
	s_or_b64 s[0:1], s[0:1], vcc
	v_readlane_b32 vcc_lo, v254, 37
	v_readlane_b32 vcc_hi, v254, 38
	s_or_b64 vcc, s[0:1], vcc
	v_cmp_ge_i32_e64 s[0:1], v100, v94
	v_cndmask_b32_e32 v64, v64, v200, vcc
	v_cmp_lt_i32_e32 vcc, v100, v96
	s_or_b64 s[0:1], vcc, s[0:1]
	v_readlane_b32 vcc_lo, v254, 39
	v_readlane_b32 vcc_hi, v254, 40
	s_or_b64 vcc, s[0:1], vcc
	v_cmp_gt_i32_e64 s[0:1], v104, v94
	v_cndmask_b32_e32 v65, v65, v200, vcc
	v_cmp_le_i32_e32 vcc, v104, v96
	s_or_b64 s[0:1], vcc, s[0:1]
	v_readlane_b32 vcc_lo, v254, 20
	v_readlane_b32 vcc_hi, v254, 21
	s_or_b64 vcc, s[0:1], vcc
	v_cmp_gt_i32_e64 s[0:1], v105, v94
	v_cndmask_b32_e32 v66, v66, v200, vcc
	v_cmp_le_i32_e32 vcc, v105, v96
	s_or_b64 s[0:1], vcc, s[0:1]
	v_readlane_b32 vcc_lo, v254, 18
	v_readlane_b32 vcc_hi, v254, 19
	s_or_b64 vcc, s[0:1], vcc
	v_cmp_gt_i32_e64 s[0:1], v106, v94
	v_cndmask_b32_e32 v67, v67, v200, vcc
	v_cmp_le_i32_e32 vcc, v106, v96
	s_or_b64 s[0:1], vcc, s[0:1]
	v_readlane_b32 vcc_lo, v254, 41
	v_readlane_b32 vcc_hi, v254, 42
	s_or_b64 vcc, s[0:1], vcc
	v_cmp_gt_i32_e64 s[0:1], v107, v94
	v_cndmask_b32_e32 v68, v68, v200, vcc
	v_cmp_le_i32_e32 vcc, v107, v96
	s_or_b64 s[0:1], vcc, s[0:1]
	v_readlane_b32 vcc_lo, v254, 22
	v_readlane_b32 vcc_hi, v254, 23
	s_or_b64 vcc, s[0:1], vcc
	v_cmp_gt_i32_e64 s[0:1], v108, v94
	v_cndmask_b32_e32 v69, v69, v200, vcc
	v_cmp_le_i32_e32 vcc, v108, v96
	s_or_b64 s[0:1], vcc, s[0:1]
	v_readlane_b32 vcc_lo, v254, 24
	v_readlane_b32 vcc_hi, v254, 25
	s_or_b64 vcc, s[0:1], vcc
	v_cmp_gt_i32_e64 s[0:1], v109, v94
	v_cndmask_b32_e32 v70, v70, v200, vcc
	v_cmp_le_i32_e32 vcc, v109, v96
	s_or_b64 s[0:1], vcc, s[0:1]
	v_readlane_b32 vcc_lo, v254, 26
	v_readlane_b32 vcc_hi, v254, 27
	s_or_b64 vcc, s[0:1], vcc
	v_cmp_gt_i32_e64 s[0:1], v110, v94
	v_cndmask_b32_e32 v71, v71, v200, vcc
	v_cmp_le_i32_e32 vcc, v110, v96
	s_or_b64 s[0:1], vcc, s[0:1]
	v_readlane_b32 vcc_lo, v254, 28
	v_readlane_b32 vcc_hi, v254, 29
	s_or_b64 vcc, s[0:1], vcc
	v_cmp_gt_i32_e64 s[0:1], v111, v94
	v_cndmask_b32_e32 v72, v72, v200, vcc
	v_cmp_le_i32_e32 vcc, v111, v96
	s_or_b64 s[0:1], vcc, s[0:1]
	v_readlane_b32 vcc_lo, v254, 32
	v_readlane_b32 vcc_hi, v254, 33
	s_or_b64 vcc, s[0:1], vcc
	v_cmp_gt_i32_e64 s[0:1], v112, v94
	v_cndmask_b32_e32 v73, v73, v200, vcc
	v_cmp_le_i32_e32 vcc, v112, v96
	s_or_b64 s[0:1], vcc, s[0:1]
	v_readlane_b32 vcc_lo, v254, 34
	v_readlane_b32 vcc_hi, v254, 35
	s_or_b64 vcc, s[0:1], vcc
	v_cmp_gt_i32_e64 s[0:1], v113, v94
	v_cndmask_b32_e32 v74, v74, v200, vcc
	v_cmp_le_i32_e32 vcc, v113, v96
	s_or_b64 s[0:1], vcc, s[0:1]
	v_readlane_b32 vcc_lo, v254, 5
	v_readlane_b32 vcc_hi, v254, 6
	s_or_b64 vcc, s[0:1], vcc
	v_cmp_gt_i32_e64 s[0:1], v114, v94
	v_cndmask_b32_e32 v75, v75, v200, vcc
	v_cmp_le_i32_e32 vcc, v114, v96
	s_or_b64 s[0:1], vcc, s[0:1]
	v_readlane_b32 vcc_lo, v254, 8
	v_readlane_b32 vcc_hi, v254, 9
	s_or_b64 vcc, s[0:1], vcc
	v_cmp_gt_i32_e64 s[0:1], v115, v94
	v_cndmask_b32_e32 v76, v76, v200, vcc
	v_cmp_le_i32_e32 vcc, v115, v96
	s_or_b64 s[0:1], vcc, s[0:1]
	v_readlane_b32 vcc_lo, v254, 30
	v_readlane_b32 vcc_hi, v254, 31
	s_or_b64 vcc, s[0:1], vcc
	v_cmp_gt_i32_e64 s[0:1], v116, v94
	v_cndmask_b32_e32 v77, v77, v200, vcc
	v_cmp_le_i32_e32 vcc, v116, v96
	s_or_b64 s[0:1], vcc, s[0:1]
	v_readlane_b32 vcc_lo, v254, 58
	v_readlane_b32 vcc_hi, v254, 59
	s_or_b64 vcc, s[0:1], vcc
	v_cmp_gt_i32_e64 s[0:1], v117, v94
	v_cndmask_b32_e32 v85, v78, v200, vcc
	v_cmp_le_i32_e32 vcc, v117, v96
	s_or_b64 s[0:1], vcc, s[0:1]
	v_readlane_b32 vcc_lo, v254, 60
	v_readlane_b32 vcc_hi, v254, 61
	s_or_b64 vcc, s[0:1], vcc
	v_readlane_b32 s0, v254, 62
	v_readlane_b32 s1, v254, 63
	s_waitcnt vmcnt(0)
	v_max3_f32 v81, v80, v64, v65
	v_max3_f32 v81, v81, v66, v67
	v_cndmask_b32_e64 v93, v48, v200, s[0:1]
	v_readlane_b32 s0, v255, 0
	v_readlane_b32 s1, v255, 1
	v_max3_f32 v81, v81, v68, v69
	v_max3_f32 v81, v81, v70, v71
	v_cndmask_b32_e64 v90, v49, v200, s[0:1]
	v_readlane_b32 s0, v255, 2
	v_readlane_b32 s1, v255, 3
	v_max3_f32 v81, v81, v72, v73
	v_max3_f32 v81, v81, v74, v75
	v_cndmask_b32_e64 v91, v50, v200, s[0:1]
	v_readlane_b32 s0, v255, 4
	v_readlane_b32 s1, v255, 5
	v_max3_f32 v81, v81, v76, v77
	v_cndmask_b32_e32 v92, v79, v200, vcc
	v_cndmask_b32_e64 v88, v51, v200, s[0:1]
	v_readlane_b32 s0, v255, 6
	v_readlane_b32 s1, v255, 7
	v_max3_f32 v78, v81, v85, v92
	v_max3_f32 v48, v78, v93, v90
	v_cndmask_b32_e64 v89, v52, v200, s[0:1]
	v_readlane_b32 s0, v255, 8
	v_readlane_b32 s1, v255, 9
	v_cmp_le_i32_e32 vcc, v118, v96
	v_max3_f32 v48, v48, v91, v88
	v_cndmask_b32_e64 v86, v53, v200, s[0:1]
	v_readlane_b32 s0, v255, 10
	v_readlane_b32 s1, v255, 11
	v_max3_f32 v48, v48, v89, v86
	v_cndmask_b32_e64 v52, v39, v200, s[6:7]
	v_cndmask_b32_e64 v87, v54, v200, s[0:1]
	v_readlane_b32 s0, v255, 12
	v_readlane_b32 s1, v255, 13
	v_cndmask_b32_e64 v51, v40, v200, s[50:51]
	v_cndmask_b32_e64 v50, v41, v200, s[52:53]
	v_cndmask_b32_e64 v83, v55, v200, s[0:1]
	v_readlane_b32 s0, v255, 14
	v_readlane_b32 s1, v255, 15
	v_max3_f32 v48, v48, v87, v83
	v_cndmask_b32_e64 v49, v42, v200, s[54:55]
	v_cndmask_b32_e64 v84, v56, v200, s[0:1]
	v_readlane_b32 s0, v255, 16
	v_readlane_b32 s1, v255, 17
	v_cndmask_b32_e64 v42, v45, v200, s[60:61]
	v_cndmask_b32_e64 v41, v46, v200, s[62:63]
	v_cndmask_b32_e64 v81, v57, v200, s[0:1]
	v_readlane_b32 s0, v255, 18
	v_readlane_b32 s1, v255, 19
	v_max3_f32 v48, v48, v84, v81
	v_cndmask_b32_e64 v40, v47, v200, s[64:65]
	v_cndmask_b32_e64 v82, v58, v200, s[0:1]
	v_readlane_b32 s0, v255, 20
	v_readlane_b32 s1, v255, 21
	v_cndmask_b32_e64 v39, v16, v200, s[66:67]
	s_nop 0
	v_cndmask_b32_e64 v78, v59, v200, s[0:1]
	v_readlane_b32 s0, v255, 22
	v_readlane_b32 s1, v255, 23
	v_max3_f32 v48, v48, v82, v78
	s_nop 0
	v_cndmask_b32_e64 v79, v60, v200, s[0:1]
	v_readlane_b32 s0, v255, 24
	v_readlane_b32 s1, v255, 25
	s_nop 1
	v_cndmask_b32_e64 v61, v61, v200, s[0:1]
	v_readlane_b32 s0, v255, 26
	v_readlane_b32 s1, v255, 27
	v_max3_f32 v48, v48, v79, v61
	s_nop 0
	v_cndmask_b32_e64 v62, v62, v200, s[0:1]
	v_readlane_b32 s0, v255, 28
	v_readlane_b32 s1, v255, 29
	s_nop 1
	v_cndmask_b32_e64 v59, v63, v200, s[0:1]
	v_readlane_b32 s0, v255, 30
	v_readlane_b32 s1, v255, 31
	v_max3_f32 v48, v48, v62, v59
	s_nop 0
	v_cndmask_b32_e64 v60, v32, v200, s[0:1]
	v_readlane_b32 s0, v255, 32
	v_readlane_b32 s1, v255, 33
	s_nop 1
	v_cndmask_b32_e64 v57, v33, v200, s[0:1]
	v_readlane_b32 s0, v255, 34
	v_readlane_b32 s1, v255, 35
	v_max3_f32 v32, v48, v60, v57
	v_cndmask_b32_e64 v48, v43, v200, s[56:57]
	v_cndmask_b32_e64 v58, v34, v200, s[0:1]
	v_readlane_b32 s0, v255, 36
	v_readlane_b32 s1, v255, 37
	v_cndmask_b32_e64 v43, v44, v200, s[58:59]
	v_cndmask_b32_e64 v34, v21, v200, s[76:77]
	v_cndmask_b32_e64 v55, v35, v200, s[0:1]
	v_readlane_b32 s0, v255, 38
	v_readlane_b32 s1, v255, 39
	v_max3_f32 v32, v32, v58, v55
	v_cndmask_b32_e64 v35, v20, v200, s[74:75]
	v_cndmask_b32_e64 v56, v36, v200, s[0:1]
	v_readlane_b32 s0, v255, 40
	v_readlane_b32 s1, v255, 41
	v_cndmask_b32_e64 v36, v19, v200, s[72:73]
	v_cndmask_b32_e64 v33, v22, v200, s[78:79]
	v_cndmask_b32_e64 v53, v37, v200, s[0:1]
	v_readlane_b32 s0, v255, 42
	v_readlane_b32 s1, v255, 43
	v_max3_f32 v32, v32, v56, v53
	v_cndmask_b32_e64 v37, v18, v200, s[70:71]
	v_cndmask_b32_e64 v54, v38, v200, s[0:1]
	v_cmp_gt_i32_e64 s[0:1], v100, v96
	s_or_b64 s[0:1], vcc, s[0:1]
	s_or_b64 vcc, s[0:1], s[42:43]
	v_cndmask_b32_e32 v0, v0, v200, vcc
	v_cmp_le_i32_e32 vcc, v119, v96
	v_cmp_gt_i32_e64 s[0:1], v119, v94
	s_or_b64 s[0:1], vcc, s[0:1]
	s_or_b64 vcc, s[0:1], s[4:5]
	v_cndmask_b32_e32 v1, v1, v200, vcc
	v_cmp_le_i32_e32 vcc, v120, v96
	v_cmp_gt_i32_e64 s[0:1], v120, v94
	s_or_b64 s[0:1], vcc, s[0:1]
	s_or_b64 vcc, s[0:1], s[48:49]
	v_cndmask_b32_e32 v2, v2, v200, vcc
	v_cmp_le_i32_e32 vcc, v121, v96
	v_cmp_gt_i32_e64 s[0:1], v121, v94
	s_or_b64 s[0:1], vcc, s[0:1]
	s_or_b64 vcc, s[0:1], s[8:9]
	v_cndmask_b32_e32 v3, v3, v200, vcc
	v_cmp_le_i32_e32 vcc, v122, v96
	v_cmp_gt_i32_e64 s[0:1], v122, v94
	s_or_b64 s[0:1], vcc, s[0:1]
	s_or_b64 vcc, s[0:1], s[10:11]
	v_cndmask_b32_e32 v4, v4, v200, vcc
	v_cmp_le_i32_e32 vcc, v123, v96
	v_cmp_gt_i32_e64 s[0:1], v123, v94
	s_or_b64 s[0:1], vcc, s[0:1]
	s_or_b64 vcc, s[0:1], s[12:13]
	v_cndmask_b32_e32 v5, v5, v200, vcc
	v_cmp_le_i32_e32 vcc, v124, v96
	v_cmp_gt_i32_e64 s[0:1], v124, v94
	s_or_b64 s[0:1], vcc, s[0:1]
	s_or_b64 vcc, s[0:1], s[14:15]
	v_cndmask_b32_e32 v6, v6, v200, vcc
	v_cmp_le_i32_e32 vcc, v125, v96
	v_cmp_gt_i32_e64 s[0:1], v125, v94
	s_or_b64 s[0:1], vcc, s[0:1]
	s_or_b64 vcc, s[0:1], s[16:17]
	v_cndmask_b32_e32 v7, v7, v200, vcc
	v_cmp_le_i32_e32 vcc, v126, v96
	v_cmp_gt_i32_e64 s[0:1], v126, v94
	s_or_b64 s[0:1], vcc, s[0:1]
	s_or_b64 vcc, s[0:1], s[18:19]
	v_cndmask_b32_e32 v8, v8, v200, vcc
	v_cmp_le_i32_e32 vcc, v127, v96
	v_cmp_gt_i32_e64 s[0:1], v127, v94
	s_or_b64 s[0:1], vcc, s[0:1]
	s_or_b64 vcc, s[0:1], s[20:21]
	v_max3_f32 v32, v32, v54, v52
	v_cndmask_b32_e32 v9, v9, v200, vcc
	v_cmp_le_i32_e32 vcc, v128, v96
	v_cmp_gt_i32_e64 s[0:1], v128, v94
	v_max3_f32 v32, v32, v51, v50
	s_or_b64 s[0:1], vcc, s[0:1]
	v_max3_f32 v32, v32, v49, v48
	s_or_b64 vcc, s[0:1], s[22:23]
	v_max3_f32 v32, v32, v43, v42
	v_cndmask_b32_e32 v10, v10, v200, vcc
	v_cmp_le_i32_e32 vcc, v129, v96
	v_cmp_gt_i32_e64 s[0:1], v129, v94
	v_max3_f32 v32, v32, v41, v40
	v_cndmask_b32_e64 v38, v17, v200, s[68:69]
	s_or_b64 s[0:1], vcc, s[0:1]
	v_max3_f32 v16, v32, v39, v38
	s_or_b64 vcc, s[0:1], s[24:25]
	v_max3_f32 v16, v16, v37, v36
	v_cndmask_b32_e32 v11, v11, v200, vcc
	v_cmp_le_i32_e32 vcc, v130, v96
	v_cmp_gt_i32_e64 s[0:1], v130, v94
	v_max3_f32 v16, v16, v35, v34
	v_cndmask_b32_e64 v32, v23, v200, s[80:81]
	s_or_b64 s[0:1], vcc, s[0:1]
	v_max3_f32 v16, v16, v33, v32
	v_cndmask_b32_e64 v23, v24, v200, s[82:83]
	v_cndmask_b32_e64 v22, v25, v200, s[84:85]
	s_or_b64 vcc, s[0:1], s[26:27]
	v_max3_f32 v16, v16, v23, v22
	v_cndmask_b32_e64 v21, v26, v200, s[86:87]
	v_cndmask_b32_e64 v20, v27, v200, s[88:89]
	v_cndmask_b32_e32 v12, v12, v200, vcc
	v_cmp_le_i32_e32 vcc, v131, v96
	v_cmp_gt_i32_e64 s[0:1], v131, v94
	v_max3_f32 v16, v16, v21, v20
	v_cndmask_b32_e64 v19, v28, v200, s[90:91]
	v_cndmask_b32_e64 v18, v29, v200, s[92:93]
	s_or_b64 s[0:1], vcc, s[0:1]
	v_max3_f32 v24, v16, v19, v18
	v_cndmask_b32_e64 v17, v30, v200, s[94:95]
	v_cndmask_b32_e64 v16, v31, v200, s[96:97]
	s_or_b64 vcc, s[0:1], s[28:29]
	v_max3_f32 v24, v24, v17, v16
	v_cndmask_b32_e32 v13, v13, v200, vcc
	v_cmp_le_i32_e32 vcc, v132, v96
	v_cmp_gt_i32_e64 s[0:1], v132, v94
	v_max3_f32 v24, v24, v0, v1
	s_or_b64 s[0:1], vcc, s[0:1]
	v_max3_f32 v24, v24, v2, v3
	s_or_b64 vcc, s[0:1], s[30:31]
	v_max3_f32 v24, v24, v4, v5
	v_cndmask_b32_e32 v14, v14, v200, vcc
	v_cmp_le_i32_e32 vcc, v133, v96
	v_cmp_gt_i32_e64 s[0:1], v133, v94
	v_max3_f32 v24, v24, v6, v7
	s_or_b64 s[0:1], vcc, s[0:1]
	v_and_b32_e32 v26, 64, v198
	v_max3_f32 v24, v24, v8, v9
	s_or_b64 vcc, s[0:1], s[34:35]
	v_xor_b32_e32 v25, 32, v198
	v_add_u32_e32 v26, 64, v26
	v_max3_f32 v24, v24, v10, v11
	v_cndmask_b32_e32 v15, v15, v200, vcc
	v_cmp_lt_i32_e32 vcc, v25, v26
	v_max3_f32 v24, v24, v12, v13
	v_max3_f32 v24, v24, v14, v15
	v_cndmask_b32_e32 v25, v198, v25, vcc
	v_lshlrev_b32_e32 v25, 2, v25
	ds_bpermute_b32 v26, v25, v24
	s_lshr_b32 s1, s39, 2
	s_mulk_i32 s1, 0x4080
	s_add_i32 s2, s1, 0x20400
	s_add_i32 s0, s44, s33
	s_waitcnt lgkmcnt(0)
	v_max_f32_e32 v26, v26, v26
	v_max_f32_e32 v24, v24, v26
	v_sub_f32_e32 v26, v64, v24
	v_mul_f32_e32 v26, 0x3fb8aa3b, v26
	v_sub_f32_e32 v28, v65, v24
	v_exp_f32_e32 v26, v26
	v_mul_f32_e32 v28, 0x3fb8aa3b, v28
	v_sub_f32_e32 v29, v66, v24
	v_exp_f32_e32 v28, v28
	v_mul_f32_e32 v29, 0x3fb8aa3b, v29
	v_sub_f32_e32 v30, v67, v24
	v_exp_f32_e32 v29, v29
	v_mul_f32_e32 v30, 0x3fb8aa3b, v30
	v_sub_f32_e32 v31, v68, v24
	v_exp_f32_e32 v30, v30
	v_mul_f32_e32 v31, 0x3fb8aa3b, v31
	v_sub_f32_e32 v44, v69, v24
	v_add_f32_e32 v27, 0, v26
	v_exp_f32_e32 v31, v31
	v_mul_f32_e32 v44, 0x3fb8aa3b, v44
	v_sub_f32_e32 v45, v70, v24
	v_add_f32_e32 v27, v28, v27
	v_exp_f32_e32 v44, v44
	v_mul_f32_e32 v45, 0x3fb8aa3b, v45
	v_sub_f32_e32 v46, v71, v24
	v_add_f32_e32 v27, v29, v27
	v_exp_f32_e32 v45, v45
	v_mul_f32_e32 v46, 0x3fb8aa3b, v46
	v_sub_f32_e32 v47, v72, v24
	v_add_f32_e32 v27, v30, v27
	v_exp_f32_e32 v46, v46
	v_mul_f32_e32 v47, 0x3fb8aa3b, v47
	v_sub_f32_e32 v63, v73, v24
	v_add_f32_e32 v27, v31, v27
	v_exp_f32_e32 v47, v47
	v_mul_f32_e32 v63, 0x3fb8aa3b, v63
	v_sub_f32_e32 v64, v74, v24
	v_add_f32_e32 v27, v44, v27
	v_exp_f32_e32 v63, v63
	v_mul_f32_e32 v64, 0x3fb8aa3b, v64
	v_sub_f32_e32 v65, v75, v24
	v_add_f32_e32 v27, v45, v27
	v_exp_f32_e32 v64, v64
	v_mul_f32_e32 v65, 0x3fb8aa3b, v65
	v_sub_f32_e32 v66, v76, v24
	v_add_f32_e32 v27, v46, v27
	v_exp_f32_e32 v65, v65
	v_mul_f32_e32 v66, 0x3fb8aa3b, v66
	v_sub_f32_e32 v67, v77, v24
	v_add_f32_e32 v27, v47, v27
	v_exp_f32_e32 v66, v66
	v_mul_f32_e32 v67, 0x3fb8aa3b, v67
	v_sub_f32_e32 v68, v85, v24
	v_add_f32_e32 v27, v63, v27
	v_exp_f32_e32 v67, v67
	v_mul_f32_e32 v68, 0x3fb8aa3b, v68
	v_sub_f32_e32 v69, v92, v24
	v_add_f32_e32 v27, v64, v27
	v_exp_f32_e32 v68, v68
	v_mul_f32_e32 v69, 0x3fb8aa3b, v69
	v_sub_f32_e32 v70, v93, v24
	v_add_f32_e32 v27, v65, v27
	v_exp_f32_e32 v69, v69
	v_mul_f32_e32 v70, 0x3fb8aa3b, v70
	v_sub_f32_e32 v71, v90, v24
	v_add_f32_e32 v27, v66, v27
	v_exp_f32_e32 v70, v70
	v_mul_f32_e32 v71, 0x3fb8aa3b, v71
	v_sub_f32_e32 v72, v91, v24
	v_add_f32_e32 v27, v67, v27
	v_exp_f32_e32 v71, v71
	v_mul_f32_e32 v72, 0x3fb8aa3b, v72
	v_sub_f32_e32 v73, v88, v24
	v_add_f32_e32 v27, v68, v27
	v_exp_f32_e32 v72, v72
	v_mul_f32_e32 v73, 0x3fb8aa3b, v73
	v_sub_f32_e32 v74, v89, v24
	v_add_f32_e32 v27, v69, v27
	v_exp_f32_e32 v73, v73
	v_mul_f32_e32 v74, 0x3fb8aa3b, v74
	v_sub_f32_e32 v75, v86, v24
	v_add_f32_e32 v27, v70, v27
	v_exp_f32_e32 v74, v74
	v_mul_f32_e32 v75, 0x3fb8aa3b, v75
	v_sub_f32_e32 v76, v87, v24
	v_add_f32_e32 v27, v71, v27
	v_exp_f32_e32 v75, v75
	v_mul_f32_e32 v76, 0x3fb8aa3b, v76
	v_sub_f32_e32 v77, v83, v24
	v_add_f32_e32 v27, v72, v27
	v_exp_f32_e32 v76, v76
	v_mul_f32_e32 v77, 0x3fb8aa3b, v77
	v_sub_f32_e32 v83, v84, v24
	v_add_f32_e32 v27, v73, v27
	v_exp_f32_e32 v77, v77
	v_mul_f32_e32 v83, 0x3fb8aa3b, v83
	v_sub_f32_e32 v81, v81, v24
	v_add_f32_e32 v27, v74, v27
	v_exp_f32_e32 v83, v83
	v_mul_f32_e32 v81, 0x3fb8aa3b, v81
	v_sub_f32_e32 v82, v82, v24
	v_add_f32_e32 v27, v75, v27
	v_exp_f32_e32 v81, v81
	v_mul_f32_e32 v82, 0x3fb8aa3b, v82
	v_sub_f32_e32 v78, v78, v24
	v_add_f32_e32 v27, v76, v27
	v_exp_f32_e32 v82, v82
	v_mul_f32_e32 v78, 0x3fb8aa3b, v78
	v_sub_f32_e32 v79, v79, v24
	v_add_f32_e32 v27, v77, v27
	v_exp_f32_e32 v78, v78
	v_mul_f32_e32 v79, 0x3fb8aa3b, v79
	v_sub_f32_e32 v61, v61, v24
	v_add_f32_e32 v27, v83, v27
	v_exp_f32_e32 v79, v79
	v_mul_f32_e32 v61, 0x3fb8aa3b, v61
	v_sub_f32_e32 v62, v62, v24
	v_add_f32_e32 v27, v81, v27
	v_exp_f32_e32 v61, v61
	v_mul_f32_e32 v62, 0x3fb8aa3b, v62
	v_sub_f32_e32 v59, v59, v24
	v_add_f32_e32 v27, v82, v27
	v_exp_f32_e32 v62, v62
	v_mul_f32_e32 v59, 0x3fb8aa3b, v59
	v_sub_f32_e32 v60, v60, v24
	v_add_f32_e32 v27, v78, v27
	v_exp_f32_e32 v59, v59
	v_mul_f32_e32 v60, 0x3fb8aa3b, v60
	v_sub_f32_e32 v57, v57, v24
	v_add_f32_e32 v27, v79, v27
	v_exp_f32_e32 v60, v60
	v_mul_f32_e32 v57, 0x3fb8aa3b, v57
	v_sub_f32_e32 v58, v58, v24
	v_add_f32_e32 v27, v61, v27
	v_exp_f32_e32 v57, v57
	v_mul_f32_e32 v58, 0x3fb8aa3b, v58
	v_sub_f32_e32 v55, v55, v24
	v_add_f32_e32 v27, v62, v27
	v_exp_f32_e32 v58, v58
	v_mul_f32_e32 v55, 0x3fb8aa3b, v55
	v_sub_f32_e32 v56, v56, v24
	v_add_f32_e32 v27, v59, v27
	v_exp_f32_e32 v55, v55
	v_mul_f32_e32 v56, 0x3fb8aa3b, v56
	v_sub_f32_e32 v53, v53, v24
	v_add_f32_e32 v27, v60, v27
	v_exp_f32_e32 v56, v56
	v_mul_f32_e32 v53, 0x3fb8aa3b, v53
	v_sub_f32_e32 v54, v54, v24
	v_add_f32_e32 v27, v57, v27
	v_exp_f32_e32 v53, v53
	v_mul_f32_e32 v54, 0x3fb8aa3b, v54
	v_sub_f32_e32 v52, v52, v24
	v_add_f32_e32 v27, v58, v27
	v_exp_f32_e32 v54, v54
	v_mul_f32_e32 v52, 0x3fb8aa3b, v52
	v_sub_f32_e32 v51, v51, v24
	v_add_f32_e32 v27, v55, v27
	v_exp_f32_e32 v52, v52
	v_mul_f32_e32 v51, 0x3fb8aa3b, v51
	v_sub_f32_e32 v50, v50, v24
	v_add_f32_e32 v27, v56, v27
	v_exp_f32_e32 v51, v51
	v_mul_f32_e32 v50, 0x3fb8aa3b, v50
	v_sub_f32_e32 v49, v49, v24
	v_add_f32_e32 v27, v53, v27
	v_exp_f32_e32 v50, v50
	v_mul_f32_e32 v49, 0x3fb8aa3b, v49
	v_sub_f32_e32 v48, v48, v24
	v_add_f32_e32 v27, v54, v27
	v_exp_f32_e32 v49, v49
	v_mul_f32_e32 v48, 0x3fb8aa3b, v48
	v_sub_f32_e32 v43, v43, v24
	v_add_f32_e32 v27, v52, v27
	v_exp_f32_e32 v48, v48
	v_mul_f32_e32 v43, 0x3fb8aa3b, v43
	v_sub_f32_e32 v42, v42, v24
	v_add_f32_e32 v27, v51, v27
	v_exp_f32_e32 v84, v43
	v_mul_f32_e32 v42, 0x3fb8aa3b, v42
	v_sub_f32_e32 v41, v41, v24
	v_add_f32_e32 v27, v50, v27
	v_exp_f32_e32 v85, v42
	v_mul_f32_e32 v41, 0x3fb8aa3b, v41
	v_sub_f32_e32 v40, v40, v24
	v_add_f32_e32 v27, v49, v27
	v_exp_f32_e32 v86, v41
	v_mul_f32_e32 v40, 0x3fb8aa3b, v40
	v_sub_f32_e32 v39, v39, v24
	v_add_f32_e32 v27, v48, v27
	v_exp_f32_e32 v87, v40
	v_mul_f32_e32 v39, 0x3fb8aa3b, v39
	v_sub_f32_e32 v38, v38, v24
	v_add_f32_e32 v27, v84, v27
	v_exp_f32_e32 v88, v39
	v_mul_f32_e32 v38, 0x3fb8aa3b, v38
	v_sub_f32_e32 v37, v37, v24
	v_add_f32_e32 v27, v85, v27
	v_exp_f32_e32 v89, v38
	v_mul_f32_e32 v37, 0x3fb8aa3b, v37
	v_sub_f32_e32 v36, v36, v24
	v_sub_f32_e32 v1, v1, v24
	v_add_f32_e32 v27, v86, v27
	v_exp_f32_e32 v90, v37
	v_mul_f32_e32 v36, 0x3fb8aa3b, v36
	v_sub_f32_e32 v35, v35, v24
	v_mul_f32_e32 v1, 0x3fb8aa3b, v1
	v_add_f32_e32 v27, v87, v27
	v_exp_f32_e32 v91, v36
	v_mul_f32_e32 v35, 0x3fb8aa3b, v35
	v_sub_f32_e32 v34, v34, v24
	v_exp_f32_e32 v142, v1
	v_sub_f32_e32 v1, v2, v24
	v_add_f32_e32 v27, v88, v27
	v_exp_f32_e32 v35, v35
	v_mul_f32_e32 v34, 0x3fb8aa3b, v34
	v_sub_f32_e32 v33, v33, v24
	v_mul_f32_e32 v1, 0x3fb8aa3b, v1
	v_add_f32_e32 v27, v89, v27
	v_exp_f32_e32 v92, v34
	v_mul_f32_e32 v33, 0x3fb8aa3b, v33
	v_sub_f32_e32 v32, v32, v24
	v_exp_f32_e32 v143, v1
	v_sub_f32_e32 v1, v3, v24
	v_add_f32_e32 v27, v90, v27
	v_exp_f32_e32 v33, v33
	v_mul_f32_e32 v32, 0x3fb8aa3b, v32
	v_sub_f32_e32 v23, v23, v24
	v_mul_f32_e32 v1, 0x3fb8aa3b, v1
	v_add_f32_e32 v27, v91, v27
	v_exp_f32_e32 v32, v32
	v_mul_f32_e32 v23, 0x3fb8aa3b, v23
	v_sub_f32_e32 v22, v22, v24
	v_exp_f32_e32 v144, v1
	v_sub_f32_e32 v1, v4, v24
	v_add_f32_e32 v27, v35, v27
	v_exp_f32_e32 v93, v23
	v_mul_f32_e32 v22, 0x3fb8aa3b, v22
	v_sub_f32_e32 v21, v21, v24
	v_mul_f32_e32 v1, 0x3fb8aa3b, v1
	v_add_f32_e32 v27, v92, v27
	v_exp_f32_e32 v94, v22
	v_mul_f32_e32 v21, 0x3fb8aa3b, v21
	v_sub_f32_e32 v20, v20, v24
	v_exp_f32_e32 v145, v1
	v_sub_f32_e32 v1, v5, v24
	v_add_f32_e32 v27, v33, v27
	v_exp_f32_e32 v95, v21
	v_mul_f32_e32 v20, 0x3fb8aa3b, v20
	v_sub_f32_e32 v19, v19, v24
	v_mul_f32_e32 v1, 0x3fb8aa3b, v1
	v_add_f32_e32 v27, v32, v27
	v_exp_f32_e32 v96, v20
	v_mul_f32_e32 v19, 0x3fb8aa3b, v19
	v_sub_f32_e32 v18, v18, v24
	v_exp_f32_e32 v146, v1
	v_sub_f32_e32 v1, v6, v24
	v_add_f32_e32 v23, v93, v27
	v_exp_f32_e32 v137, v19
	v_mul_f32_e32 v18, 0x3fb8aa3b, v18
	v_sub_f32_e32 v17, v17, v24
	v_mul_f32_e32 v1, 0x3fb8aa3b, v1
	v_add_f32_e32 v22, v94, v23
	v_exp_f32_e32 v138, v18
	v_mul_f32_e32 v17, 0x3fb8aa3b, v17
	v_sub_f32_e32 v16, v16, v24
	v_exp_f32_e32 v147, v1
	v_sub_f32_e32 v1, v7, v24
	v_add_f32_e32 v21, v95, v22
	v_exp_f32_e32 v139, v17
	v_mul_f32_e32 v16, 0x3fb8aa3b, v16
	v_sub_f32_e32 v0, v0, v24
	v_mul_f32_e32 v1, 0x3fb8aa3b, v1
	v_add_f32_e32 v20, v96, v21
	v_exp_f32_e32 v140, v16
	v_mul_f32_e32 v0, 0x3fb8aa3b, v0
	v_exp_f32_e32 v148, v1
	v_sub_f32_e32 v1, v8, v24
	v_add_f32_e32 v19, v137, v20
	v_exp_f32_e32 v141, v0
	v_mul_f32_e32 v1, 0x3fb8aa3b, v1
	v_add_f32_e32 v18, v138, v19
	v_exp_f32_e32 v149, v1
	v_sub_f32_e32 v1, v9, v24
	v_add_f32_e32 v17, v139, v18
	v_mul_f32_e32 v1, 0x3fb8aa3b, v1
	v_add_f32_e32 v16, v140, v17
	v_exp_f32_e32 v150, v1
	v_sub_f32_e32 v1, v10, v24
	v_add_f32_e32 v0, v141, v16
	v_mul_f32_e32 v1, 0x3fb8aa3b, v1
	v_add_f32_e32 v0, v142, v0
	v_exp_f32_e32 v151, v1
	v_sub_f32_e32 v1, v11, v24
	v_add_f32_e32 v0, v143, v0
	v_mul_f32_e32 v1, 0x3fb8aa3b, v1
	v_add_f32_e32 v0, v144, v0
	v_exp_f32_e32 v152, v1
	v_sub_f32_e32 v1, v12, v24
	v_add_f32_e32 v0, v145, v0
	v_mul_f32_e32 v1, 0x3fb8aa3b, v1
	v_add_f32_e32 v0, v146, v0
	v_exp_f32_e32 v153, v1
	v_sub_f32_e32 v1, v13, v24
	v_add_f32_e32 v0, v147, v0
	v_mul_f32_e32 v1, 0x3fb8aa3b, v1
	v_add_f32_e32 v0, v148, v0
	v_exp_f32_e32 v154, v1
	v_sub_f32_e32 v1, v14, v24
	v_add_f32_e32 v0, v149, v0
	v_mul_f32_e32 v1, 0x3fb8aa3b, v1
	v_add_f32_e32 v0, v150, v0
	v_exp_f32_e32 v155, v1
	v_sub_f32_e32 v1, v15, v24
	v_add_f32_e32 v0, v151, v0
	v_mul_f32_e32 v1, 0x3fb8aa3b, v1
	v_add_f32_e32 v0, v152, v0
	v_exp_f32_e32 v156, v1
	v_add_f32_e32 v0, v153, v0
	v_add_f32_e32 v0, v154, v0
	v_add_f32_e32 v0, v155, v0
	v_add_f32_e32 v0, v156, v0
	ds_bpermute_b32 v1, v25, v0
	v_cvt_pk_bf16_f32 v2, v31, v44
	v_add_u32_e32 v44, 0x9000, v136
	ds_read2_b64 v[4:7], v44 offset1:2
	ds_read2_b64 v[36:39], v44 offset0:4 offset1:6
	v_cvt_pk_bf16_f32 v3, v45, v46
	s_waitcnt lgkmcnt(2)
	v_add_f32_e32 v0, v0, v1
	v_sub_f32_e32 v1, v80, v24
	v_mul_f32_e32 v1, 0x3fb8aa3b, v1
	v_exp_f32_e32 v1, v1
	v_add_u32_e32 v45, 0xd000, v136
	v_cvt_pk_bf16_f32 v40, v47, v63
	v_cvt_pk_bf16_f32 v41, v64, v65
	v_add_f32_e32 v34, v1, v0
	v_cvt_pk_bf16_f32 v0, v26, v28
	v_cvt_pk_bf16_f32 v1, v29, v30
	v_cvt_pk_bf16_f32 v42, v66, v67
	v_cvt_pk_bf16_f32 v43, v68, v69
	s_waitcnt lgkmcnt(1)
	v_mfma_f32_32x32x16_bf16 v[16:31], v[4:7], v[0:3], 0
	ds_read2_b64 v[4:7], v45 offset0:96 offset1:98
	s_and_b32 s0, s0, 0xc0
	s_mov_b64 vcc, s[46:47]
	v_readlane_b32 s1, v254, 36
	s_add_i32 s33, s33, 64
	v_mov_b32_e32 v203, 0
	v_lshl_add_u64 v[192:193], s[2:3], 0, v[98:99]
	v_lshlrev_b64 v[192:193], 9, v[192:193]
	v_lshl_add_u64 v[192:193], vcc, 0, v[192:193]
	s_lshl_b32 s2, s0, 1
	v_lshl_add_u64 v[192:193], v[192:193], 0, s[2:3]
	s_and_b32 s0, s38, 4
	s_or_b32 s0, s0, s1
	s_lshr_b32 s0, s0, 2
	v_lshlrev_b32_e32 v202, 1, v100
	v_lshl_add_u64 v[192:193], v[192:193], 0, v[202:203]
	s_mul_i32 s2, s0, 0x4080
	v_lshl_add_u64 v[194:195], s[2:3], 0, v[98:99]
	s_and_b32 s0, s33, 0xc0
	v_or_b32_e32 v196, s0, v134
	v_lshlrev_b64 v[194:195], 9, v[194:195]
	v_lshl_add_u64 v[194:195], vcc, 0, v[194:195]
	v_lshlrev_b32_e32 v202, 1, v196
	v_lshl_add_u64 v[194:195], v[194:195], 0, v[202:203]
	global_load_dwordx2 v[160:161], v[192:193], off
	global_load_dwordx2 v[162:163], v[192:193], off offset:16
	global_load_dwordx2 v[164:165], v[192:193], off offset:32
	global_load_dwordx2 v[166:167], v[192:193], off offset:48
	global_load_dwordx2 v[168:169], v[192:193], off offset:64
	global_load_dwordx2 v[170:171], v[192:193], off offset:80
	global_load_dwordx2 v[172:173], v[192:193], off offset:96
	global_load_dwordx2 v[174:175], v[192:193], off offset:112
	global_load_dwordx4 v[176:179], v[194:195], off
	global_load_dwordx4 v[180:183], v[194:195], off offset:32
	global_load_dwordx4 v[184:187], v[194:195], off offset:64
	global_load_dwordx4 v[188:191], v[194:195], off offset:96
	v_rcp_f32_e32 v34, v34
	s_waitcnt lgkmcnt(1)
	v_mfma_f32_32x32x16_bf16 v[16:31], v[36:39], v[40:43], v[16:31]
	ds_read2_b64 v[36:39], v45 offset0:100 offset1:102
	s_waitcnt lgkmcnt(1)
	v_mfma_f32_32x32x16_bf16 v[0:15], v[4:7], v[0:3], 0
	s_waitcnt lgkmcnt(0)
	v_mfma_f32_32x32x16_bf16 v[0:15], v[36:39], v[40:43], v[0:15]
	ds_read2_b64 v[40:43], v44 offset0:8 offset1:10
	v_cvt_pk_bf16_f32 v36, v70, v71
	v_cvt_pk_bf16_f32 v37, v72, v73
	v_cvt_pk_bf16_f32 v38, v74, v75
	v_cvt_pk_bf16_f32 v39, v76, v77
	s_waitcnt lgkmcnt(0)
	s_nop 0
	v_mfma_f32_32x32x16_bf16 v[16:31], v[40:43], v[36:39], v[16:31]
	ds_read2_b64 v[40:43], v45 offset0:104 offset1:106
	s_waitcnt lgkmcnt(0)
	v_mfma_f32_32x32x16_bf16 v[0:15], v[40:43], v[36:39], v[0:15]
	ds_read2_b64 v[40:43], v44 offset0:12 offset1:14
	v_cvt_pk_bf16_f32 v36, v83, v81
	v_cvt_pk_bf16_f32 v37, v82, v78
	v_cvt_pk_bf16_f32 v38, v79, v61
	v_cvt_pk_bf16_f32 v39, v62, v59
	s_waitcnt lgkmcnt(0)
	s_nop 0
	v_mfma_f32_32x32x16_bf16 v[16:31], v[40:43], v[36:39], v[16:31]
	ds_read2_b64 v[40:43], v45 offset0:108 offset1:110
	s_waitcnt lgkmcnt(0)
	v_mfma_f32_32x32x16_bf16 v[0:15], v[40:43], v[36:39], v[0:15]
	ds_read2_b64 v[40:43], v44 offset0:16 offset1:18
	v_cvt_pk_bf16_f32 v36, v60, v57
	v_cvt_pk_bf16_f32 v37, v58, v55
	v_cvt_pk_bf16_f32 v38, v56, v53
	v_cvt_pk_bf16_f32 v39, v54, v52
	s_waitcnt lgkmcnt(0)
	s_nop 0
	v_mfma_f32_32x32x16_bf16 v[16:31], v[40:43], v[36:39], v[16:31]
	ds_read2_b64 v[40:43], v45 offset0:112 offset1:114
	s_waitcnt lgkmcnt(0)
	v_mfma_f32_32x32x16_bf16 v[0:15], v[40:43], v[36:39], v[0:15]
	ds_read2_b64 v[40:43], v44 offset0:20 offset1:22
	v_cvt_pk_bf16_f32 v36, v51, v50
	v_cvt_pk_bf16_f32 v37, v49, v48
	v_cvt_pk_bf16_f32 v38, v84, v85
	v_cvt_pk_bf16_f32 v39, v86, v87
	s_waitcnt lgkmcnt(0)
	s_nop 0
	v_mfma_f32_32x32x16_bf16 v[16:31], v[40:43], v[36:39], v[16:31]
	ds_read2_b64 v[40:43], v45 offset0:116 offset1:118
	s_waitcnt lgkmcnt(0)
	v_mfma_f32_32x32x16_bf16 v[0:15], v[40:43], v[36:39], v[0:15]
	ds_read2_b64 v[40:43], v44 offset0:24 offset1:26
	v_cvt_pk_bf16_f32 v36, v88, v89
	v_cvt_pk_bf16_f32 v37, v90, v91
	v_cvt_pk_bf16_f32 v38, v35, v92
	v_cvt_pk_bf16_f32 v39, v33, v32
	s_waitcnt lgkmcnt(0)
	s_nop 0
	v_mfma_f32_32x32x16_bf16 v[16:31], v[40:43], v[36:39], v[16:31]
	ds_read2_b64 v[40:43], v45 offset0:120 offset1:122
	s_waitcnt lgkmcnt(0)
	v_mfma_f32_32x32x16_bf16 v[0:15], v[40:43], v[36:39], v[0:15]
	ds_read2_b64 v[40:43], v44 offset0:28 offset1:30
	v_cvt_pk_bf16_f32 v36, v93, v94
	v_cvt_pk_bf16_f32 v37, v95, v96
	v_cvt_pk_bf16_f32 v38, v137, v138
	v_cvt_pk_bf16_f32 v39, v139, v140
	s_waitcnt lgkmcnt(0)
	s_nop 0
	v_mfma_f32_32x32x16_bf16 v[16:31], v[40:43], v[36:39], v[16:31]
	ds_read2_b64 v[40:43], v45 offset0:124 offset1:126
	s_waitcnt lgkmcnt(0)
	v_mfma_f32_32x32x16_bf16 v[0:15], v[40:43], v[36:39], v[0:15]
	ds_read2_b64 v[40:43], v44 offset0:32 offset1:34
	v_cvt_pk_bf16_f32 v36, v141, v142
	v_cvt_pk_bf16_f32 v37, v143, v144
	v_cvt_pk_bf16_f32 v38, v145, v146
	v_cvt_pk_bf16_f32 v39, v147, v148
	s_waitcnt lgkmcnt(0)
	s_nop 0
	v_mfma_f32_32x32x16_bf16 v[16:31], v[40:43], v[36:39], v[16:31]
	ds_read2_b64 v[40:43], v45 offset0:128 offset1:130
	s_add_u32 s36, s36, 4
	s_addc_u32 s37, s37, 0
	s_mov_b64 s[0:1], 0x80
	s_cmp_eq_u32 s38, 8
	s_waitcnt lgkmcnt(0)
	v_mfma_f32_32x32x16_bf16 v[0:15], v[40:43], v[36:39], v[0:15]
	ds_read2_b64 v[40:43], v44 offset0:36 offset1:38
	v_cvt_pk_bf16_f32 v36, v149, v150
	v_cvt_pk_bf16_f32 v37, v151, v152
	v_cvt_pk_bf16_f32 v38, v153, v154
	v_cvt_pk_bf16_f32 v39, v155, v156
	s_waitcnt lgkmcnt(0)
	s_nop 0
	v_mfma_f32_32x32x16_bf16 v[16:31], v[40:43], v[36:39], v[16:31]
	ds_read2_b64 v[40:43], v45 offset0:132 offset1:134
	s_waitcnt lgkmcnt(0)
	v_mfma_f32_32x32x16_bf16 v[0:15], v[40:43], v[36:39], v[0:15]
	s_nop 0
	s_nop 0
	s_nop 6
	v_pk_mul_f32 v[16:17], v[16:17], v[34:35] op_sel_hi:[1,0]
	v_pk_mul_f32 v[18:19], v[18:19], v[34:35] op_sel_hi:[1,0]
	s_nop 0
	v_pk_mul_f32 v[0:1], v[0:1], v[34:35] op_sel_hi:[1,0]
	v_pk_mul_f32 v[2:3], v[2:3], v[34:35] op_sel_hi:[1,0]
	v_lshl_add_u64 v[204:205], v[102:103], 0, v[206:207]
	s_waitcnt vmcnt(11)
	v_lshlrev_b32_e32 v50, 16, v160
	v_and_b32_e32 v51, 0xffff0000, v160
	v_lshlrev_b32_e32 v48, 16, v161
	v_and_b32_e32 v49, 0xffff0000, v161
	v_pk_mul_f32 v[16:17], v[16:17], v[50:51]
	v_pk_mul_f32 v[18:19], v[18:19], v[48:49]
	v_cvt_pk_bf16_f32 v208, v16, v17
	v_cvt_pk_bf16_f32 v209, v18, v19
	v_pk_mul_f32 v[16:17], v[20:21], v[34:35] op_sel_hi:[1,0]
	s_waitcnt vmcnt(10)
	v_lshlrev_b32_e32 v18, 16, v162
	v_and_b32_e32 v19, 0xffff0000, v162
	v_pk_mul_f32 v[16:17], v[16:17], v[18:19]
	v_pk_mul_f32 v[18:19], v[22:23], v[34:35] op_sel_hi:[1,0]
	v_lshlrev_b32_e32 v20, 16, v163
	v_and_b32_e32 v21, 0xffff0000, v163
	v_pk_mul_f32 v[18:19], v[18:19], v[20:21]
	v_cvt_pk_bf16_f32 v210, v16, v17
	v_cvt_pk_bf16_f32 v211, v18, v19
	s_nop 1
	v_permlane32_swap_b32_e32 v208, v210
	v_permlane32_swap_b32_e32 v209, v211
	global_store_dwordx4 v[204:205], v[208:211], off offset:-64
	v_pk_mul_f32 v[16:17], v[24:25], v[34:35] op_sel_hi:[1,0]
	s_waitcnt vmcnt(10)
	v_lshlrev_b32_e32 v18, 16, v164
	v_and_b32_e32 v19, 0xffff0000, v164
	v_pk_mul_f32 v[16:17], v[16:17], v[18:19]
	v_pk_mul_f32 v[18:19], v[26:27], v[34:35] op_sel_hi:[1,0]
	v_lshlrev_b32_e32 v20, 16, v165
	v_and_b32_e32 v21, 0xffff0000, v165
	v_pk_mul_f32 v[18:19], v[18:19], v[20:21]
	v_cvt_pk_bf16_f32 v212, v16, v17
	v_cvt_pk_bf16_f32 v213, v18, v19
	v_pk_mul_f32 v[16:17], v[28:29], v[34:35] op_sel_hi:[1,0]
	s_waitcnt vmcnt(9)
	v_lshlrev_b32_e32 v18, 16, v166
	v_and_b32_e32 v19, 0xffff0000, v166
	v_pk_mul_f32 v[16:17], v[16:17], v[18:19]
	v_pk_mul_f32 v[18:19], v[30:31], v[34:35] op_sel_hi:[1,0]
	v_lshlrev_b32_e32 v20, 16, v167
	v_and_b32_e32 v21, 0xffff0000, v167
	v_pk_mul_f32 v[18:19], v[18:19], v[20:21]
	v_cvt_pk_bf16_f32 v214, v16, v17
	v_cvt_pk_bf16_f32 v215, v18, v19
	s_nop 1
	v_permlane32_swap_b32_e32 v212, v214
	v_permlane32_swap_b32_e32 v213, v215
	global_store_dwordx4 v[204:205], v[212:215], off offset:-32
	s_waitcnt vmcnt(9)
	v_lshlrev_b32_e32 v16, 16, v168
	v_and_b32_e32 v17, 0xffff0000, v168
	v_pk_mul_f32 v[0:1], v[0:1], v[16:17]
	v_lshlrev_b32_e32 v16, 16, v169
	v_and_b32_e32 v17, 0xffff0000, v169
	v_pk_mul_f32 v[2:3], v[2:3], v[16:17]
	v_cvt_pk_bf16_f32 v216, v0, v1
	v_cvt_pk_bf16_f32 v217, v2, v3
	v_pk_mul_f32 v[0:1], v[4:5], v[34:35] op_sel_hi:[1,0]
	s_waitcnt vmcnt(8)
	v_lshlrev_b32_e32 v2, 16, v170
	v_and_b32_e32 v3, 0xffff0000, v170
	v_pk_mul_f32 v[0:1], v[0:1], v[2:3]
	v_pk_mul_f32 v[2:3], v[6:7], v[34:35] op_sel_hi:[1,0]
	v_lshlrev_b32_e32 v4, 16, v171
	v_and_b32_e32 v5, 0xffff0000, v171
	v_pk_mul_f32 v[2:3], v[2:3], v[4:5]
	v_cvt_pk_bf16_f32 v218, v0, v1
	v_cvt_pk_bf16_f32 v219, v2, v3
	s_nop 1
	v_permlane32_swap_b32_e32 v216, v218
	v_permlane32_swap_b32_e32 v217, v219
	global_store_dwordx4 v[204:205], v[216:219], off
	v_pk_mul_f32 v[0:1], v[8:9], v[34:35] op_sel_hi:[1,0]
	s_waitcnt vmcnt(8)
	v_lshlrev_b32_e32 v2, 16, v172
	v_and_b32_e32 v3, 0xffff0000, v172
	v_pk_mul_f32 v[0:1], v[0:1], v[2:3]
	v_pk_mul_f32 v[2:3], v[10:11], v[34:35] op_sel_hi:[1,0]
	v_lshlrev_b32_e32 v4, 16, v173
	v_and_b32_e32 v5, 0xffff0000, v173
	v_pk_mul_f32 v[2:3], v[2:3], v[4:5]
	v_cvt_pk_bf16_f32 v220, v0, v1
	v_cvt_pk_bf16_f32 v221, v2, v3
	v_pk_mul_f32 v[0:1], v[12:13], v[34:35] op_sel_hi:[1,0]
	s_waitcnt vmcnt(7)
	v_lshlrev_b32_e32 v2, 16, v174
	v_and_b32_e32 v3, 0xffff0000, v174
	v_pk_mul_f32 v[0:1], v[0:1], v[2:3]
	v_pk_mul_f32 v[2:3], v[14:15], v[34:35] op_sel_hi:[1,0]
	v_lshlrev_b32_e32 v4, 16, v175
	v_and_b32_e32 v5, 0xffff0000, v175
	v_pk_mul_f32 v[2:3], v[2:3], v[4:5]
	v_cvt_pk_bf16_f32 v222, v0, v1
	v_cvt_pk_bf16_f32 v223, v2, v3
	s_nop 1
	v_permlane32_swap_b32_e32 v220, v222
	v_permlane32_swap_b32_e32 v221, v223
	global_store_dwordx4 v[204:205], v[220:223], off offset:32
	v_lshl_add_u64 v[102:103], v[102:103], 0, s[0:1]
	s_waitcnt vmcnt(4)
	v_mov_b32_e32 v80, v176
	v_mov_b32_e32 v81, v177
	v_mov_b32_e32 v82, v178
	v_mov_b32_e32 v83, v179
	v_mov_b32_e32 v84, v180
	v_mov_b32_e32 v85, v181
	v_mov_b32_e32 v86, v182
	v_mov_b32_e32 v87, v183
	v_mov_b32_e32 v88, v184
	v_mov_b32_e32 v89, v185
	v_mov_b32_e32 v90, v186
	v_mov_b32_e32 v91, v187
	v_mov_b32_e32 v92, v188
	v_mov_b32_e32 v93, v189
	v_mov_b32_e32 v94, v190
	v_mov_b32_e32 v95, v191
	s_cbranch_scc0 .LBB0_2056
	v_readlane_b32 s91, v254, 17
	v_readlane_b32 s24, v254, 52
	s_mov_b32 s37, s3
	s_movk_i32 s25, 0x90
	s_branch .LBB0_1999
